# s5_prompt: time segments rebalanced to 480/480/480/624 tokens (wave 3 has no pass 1)
# baseline (speedup 1.0000x reference)
.LBB0_457:
	s_or_b64 exec, exec, s[2:3]
	s_waitcnt vmcnt(8)
	v_mul_f32_e32 v43, v36, v39
	v_mul_f32_e32 v32, 0x3fb8aa3b, v43
	s_mov_b32 s2, 0x3fb8aa3b
	v_fma_f32 v33, v43, s2, -v32
	v_rndne_f32_e32 v34, v32
	v_fmac_f32_e32 v33, 0x32a5705f, v43
	v_sub_f32_e32 v32, v32, v34
	v_add_f32_e32 v32, v32, v33
	v_exp_f32_e32 v32, v32
	v_cvt_i32_f32_e32 v33, v34
	s_mov_b32 s2, 0xc2ce8ed0
	v_cmp_ngt_f32_e32 vcc, s2, v43
	s_mov_b32 s2, 0x42b17218
	v_ldexp_f32 v32, v32, v33
	v_cndmask_b32_e32 v32, 0, v32, vcc
	v_cmp_nlt_f32_e32 vcc, s2, v43
	s_brev_b32 s2, 1
	v_xor_b32_e32 v38, v38, v46
	v_cndmask_b32_e32 v33, v233, v32, vcc
	v_mul_f32_e32 v32, v41, v41
	v_fmamk_f32 v34, v32, 0xb94c1982, v224
	v_fmaak_f32 v34, v32, v34, 0xbe2aaa9d
	v_mul_f32_e32 v34, v32, v34
	v_fmac_f32_e32 v41, v41, v34
	v_fmamk_f32 v34, v32, 0x37d75334, v226
	v_fmaak_f32 v34, v32, v34, 0x3d2aabf7
	v_fmaak_f32 v34, v32, v34, 0xbf000004
	v_fma_f32 v32, v32, v34, 1.0
	v_and_b32_e32 v34, 1, v40
	v_cmp_eq_u32_e32 vcc, 0, v34
	v_lshlrev_b32_e32 v34, 30, v40
	s_ashr_i32 s35, s30, 6
	v_cndmask_b32_e64 v32, -v41, v32, vcc
	v_bitop3_b32 v32, v34, v32, s2 bitop3:0x6c
	v_mul_f32_e32 v34, v45, v45
	v_fmamk_f32 v39, v34, 0xb94c1982, v224
	v_fmaak_f32 v39, v34, v39, 0xbe2aaa9d
	v_mul_f32_e32 v39, v34, v39
	v_fmac_f32_e32 v45, v45, v39
	v_fmamk_f32 v39, v34, 0x37d75334, v226
	v_fmaak_f32 v39, v34, v39, 0x3d2aabf7
	v_fmaak_f32 v39, v34, v39, 0xbf000004
	v_fma_f32 v34, v34, v39, 1.0
	v_and_b32_e32 v39, 1, v44
	v_cmp_eq_u32_e64 s[8:9], 0, v39
	v_lshlrev_b32_e32 v39, 30, v44
	v_and_b32_e32 v39, 0x80000000, v39
	s_movk_i32 s2, 0x1f8
	v_cndmask_b32_e64 v34, v34, v45, s[8:9]
	v_xor_b32_e32 v38, v38, v39
	v_cmp_class_f32_e64 vcc, v46, s2
	v_xor_b32_e32 v34, v38, v34
	v_mov_b32_e32 v44, v37
	v_cndmask_b32_e32 v34, v236, v34, vcc
	v_cndmask_b32_e32 v35, v236, v32, vcc
	v_mul_f32_e32 v34, v33, v34
	v_fma_f32 v40, v33, v35, -1.0
	v_mov_b32_e32 v41, v34
	v_pk_mul_f32 v[38:39], v[36:37], v[36:37]
	v_pk_mul_f32 v[44:45], v[44:45], v[40:41] op_sel:[0,1] op_sel_hi:[0,0]
	v_pk_fma_f32 v[48:49], v[36:37], v[40:41], v[44:45]
	v_pk_fma_f32 v[36:37], v[36:37], v[40:41], v[44:45] op_sel_hi:[0,1,1] neg_lo:[0,0,1] neg_hi:[0,0,1]
	v_pk_add_f32 v[38:39], v[38:39], v[38:39] op_sel:[0,1] op_sel_hi:[0,1]
	v_mul_f32_e32 v32, v33, v35
	v_div_scale_f32 v33, s[2:3], v39, v39, v37
	v_rcp_f32_e32 v35, v33
	s_mul_i32 s20, s35, 0x1e0
	s_ashr_i32 s17, s31, 4
	s_add_i32 s8, s20, 0x1e0
	v_fma_f32 v36, -v33, v35, 1.0
	v_fmac_f32_e32 v35, v36, v35
	v_div_scale_f32 v36, vcc, v37, v39, v37
	v_mul_f32_e32 v40, v36, v35
	v_fma_f32 v41, -v33, v40, v36
	v_fmac_f32_e32 v40, v41, v35
	v_fma_f32 v33, -v33, v40, v36
	v_div_fmas_f32 v33, v33, v35, v40
	v_div_fixup_f32 v41, v33, v39, v37
	v_div_scale_f32 v33, s[2:3], v38, v38, v48
	v_rcp_f32_e32 v35, v33
	s_cmp_eq_u32 s35, 3
	s_cselect_b64 s[2:3], -1, 0
	s_and_b64 s[4:5], s[2:3], exec
	v_fma_f32 v36, -v33, v35, 1.0
	v_fmac_f32_e32 v35, v36, v35
	v_div_scale_f32 v36, vcc, v48, v38, v48
	v_mul_f32_e32 v37, v36, v35
	v_fma_f32 v39, -v33, v37, v36
	v_fmac_f32_e32 v37, v39, v35
	v_fma_f32 v33, -v33, v37, v36
	v_div_fmas_f32 v33, v33, v35, v37
	v_div_fixup_f32 v40, v33, v38, v48
	s_waitcnt vmcnt(0)
	v_pk_mul_f32 v[38:39], v[28:29], v[40:41] op_sel:[0,1] op_sel_hi:[0,0]
	v_pk_fma_f32 v[36:37], v[24:25], v[40:41], v[38:39] neg_lo:[0,0,1] neg_hi:[0,0,1]
	v_pk_fma_f32 v[38:39], v[24:25], v[40:41], v[38:39] op_sel_hi:[0,1,1]
	v_mov_b32_e32 v37, v39
	v_pk_mul_f32 v[38:39], v[28:29], v[40:41] op_sel:[1,1] op_sel_hi:[1,0]
	v_mov_b32_e32 v28, v25
	v_pk_fma_f32 v[28:29], v[28:29], v[40:41], v[38:39] neg_lo:[0,0,1] neg_hi:[0,0,1]
	v_pk_fma_f32 v[24:25], v[24:25], v[40:41], v[38:39] op_sel:[1,0,0]
	v_pk_mul_f32 v[38:39], v[30:31], v[40:41] op_sel:[0,1] op_sel_hi:[0,0]
	v_mov_b32_e32 v29, v25
	v_pk_fma_f32 v[24:25], v[26:27], v[40:41], v[38:39] neg_lo:[0,0,1] neg_hi:[0,0,1]
	v_pk_fma_f32 v[38:39], v[26:27], v[40:41], v[38:39] op_sel_hi:[0,1,1]
	v_mov_b32_e32 v26, v31
	v_pk_mul_f32 v[30:31], v[26:27], v[40:41] op_sel:[0,1] op_sel_hi:[0,0]
	v_mov_b32_e32 v26, v27
	v_mov_b32_e32 v38, v27
	v_mov_b32_e32 v25, v39
	v_pk_fma_f32 v[26:27], v[26:27], v[40:41], v[30:31] neg_lo:[0,0,1] neg_hi:[0,0,1]
	v_pk_fma_f32 v[30:31], v[38:39], v[40:41], v[30:31] op_sel_hi:[0,1,1]
	v_pk_mul_f32 v[38:39], v[40:41], v[20:21] op_sel:[1,0] op_sel_hi:[0,0]
	v_mov_b32_e32 v27, v31
	v_pk_fma_f32 v[30:31], v[16:17], v[40:41], v[38:39] neg_lo:[0,0,1] neg_hi:[0,0,1]
	v_pk_fma_f32 v[38:39], v[16:17], v[40:41], v[38:39] op_sel_hi:[0,1,1]
	v_mov_b32_e32 v16, v21
	v_pk_mul_f32 v[20:21], v[40:41], v[16:17] op_sel:[1,0] op_sel_hi:[0,0]
	v_mov_b32_e32 v16, v17
	v_mov_b32_e32 v38, v17
	v_mov_b32_e32 v31, v39
	v_pk_fma_f32 v[16:17], v[16:17], v[40:41], v[20:21] neg_lo:[0,0,1] neg_hi:[0,0,1]
	v_pk_fma_f32 v[20:21], v[38:39], v[40:41], v[20:21] op_sel_hi:[0,1,1]
	v_pk_mul_f32 v[38:39], v[40:41], v[22:23] op_sel:[1,0] op_sel_hi:[0,0]
	v_mov_b32_e32 v17, v21
	v_pk_fma_f32 v[20:21], v[18:19], v[40:41], v[38:39] neg_lo:[0,0,1] neg_hi:[0,0,1]
	v_pk_fma_f32 v[38:39], v[18:19], v[40:41], v[38:39] op_sel_hi:[0,1,1]
	v_mov_b32_e32 v18, v23
	v_pk_mul_f32 v[22:23], v[40:41], v[18:19] op_sel:[1,0] op_sel_hi:[0,0]
	v_mov_b32_e32 v18, v19
	v_mov_b32_e32 v38, v19
	v_mov_b32_e32 v21, v39
	v_pk_fma_f32 v[18:19], v[18:19], v[40:41], v[22:23] neg_lo:[0,0,1] neg_hi:[0,0,1]
	v_pk_fma_f32 v[22:23], v[38:39], v[40:41], v[22:23] op_sel_hi:[0,1,1]
	v_pk_mul_f32 v[38:39], v[40:41], v[12:13] op_sel:[1,0] op_sel_hi:[0,0]
	v_mov_b32_e32 v19, v23
	v_pk_fma_f32 v[22:23], v[40:41], v[8:9], v[38:39] neg_lo:[0,0,1] neg_hi:[0,0,1]
	v_pk_fma_f32 v[38:39], v[40:41], v[8:9], v[38:39] op_sel_hi:[1,0,1]
	v_mov_b32_e32 v8, v13
	v_pk_mul_f32 v[12:13], v[40:41], v[8:9] op_sel:[1,0] op_sel_hi:[0,0]
	v_mov_b32_e32 v8, v9
	v_mov_b32_e32 v23, v39
	v_pk_fma_f32 v[38:39], v[40:41], v[8:9], v[12:13] op_sel_hi:[1,0,1]
	v_pk_fma_f32 v[8:9], v[40:41], v[8:9], v[12:13] op_sel_hi:[1,0,1] neg_lo:[0,0,1] neg_hi:[0,0,1]
	v_pk_mul_f32 v[12:13], v[40:41], v[14:15] op_sel:[1,0] op_sel_hi:[0,0]
	v_mov_b32_e32 v9, v39
	v_pk_fma_f32 v[38:39], v[40:41], v[10:11], v[12:13] op_sel_hi:[1,0,1]
	v_pk_fma_f32 v[12:13], v[40:41], v[10:11], v[12:13] op_sel_hi:[1,0,1] neg_lo:[0,0,1] neg_hi:[0,0,1]
	v_mov_b32_e32 v10, v15
	v_pk_mul_f32 v[14:15], v[40:41], v[10:11] op_sel:[1,0] op_sel_hi:[0,0]
	v_mov_b32_e32 v10, v11
	v_mov_b32_e32 v13, v39
	v_pk_fma_f32 v[38:39], v[40:41], v[10:11], v[14:15] op_sel_hi:[1,0,1]
	v_pk_fma_f32 v[10:11], v[40:41], v[10:11], v[14:15] op_sel_hi:[1,0,1] neg_lo:[0,0,1] neg_hi:[0,0,1]
	v_pk_mul_f32 v[14:15], v[40:41], v[4:5] op_sel:[1,0] op_sel_hi:[0,0]
	v_mov_b32_e32 v11, v39
	v_pk_fma_f32 v[38:39], v[40:41], v[0:1], v[14:15] op_sel_hi:[1,0,1]
	v_pk_fma_f32 v[14:15], v[40:41], v[0:1], v[14:15] op_sel_hi:[1,0,1] neg_lo:[0,0,1] neg_hi:[0,0,1]
	v_mov_b32_e32 v0, v5
	v_pk_mul_f32 v[4:5], v[40:41], v[0:1] op_sel:[1,0] op_sel_hi:[0,0]
	v_mov_b32_e32 v0, v1
	v_mov_b32_e32 v15, v39
	v_pk_fma_f32 v[38:39], v[40:41], v[0:1], v[4:5] op_sel_hi:[1,0,1]
	v_pk_fma_f32 v[4:5], v[40:41], v[0:1], v[4:5] op_sel_hi:[1,0,1] neg_lo:[0,0,1] neg_hi:[0,0,1]
	v_pk_mul_f32 v[0:1], v[40:41], v[6:7] op_sel:[1,0] op_sel_hi:[0,0]
	s_mul_i32 s34, s17, 0x810
	s_mul_i32 s4, s17, 0x912000
	v_mov_b32_e32 v5, v39
	v_pk_fma_f32 v[44:45], v[40:41], v[2:3], v[0:1] op_sel_hi:[1,0,1]
	v_pk_fma_f32 v[38:39], v[40:41], v[2:3], v[0:1] op_sel_hi:[1,0,1] neg_lo:[0,0,1] neg_hi:[0,0,1]
	v_mov_b32_e32 v0, v7
	s_cselect_b32 s21, 0x810, s8
	s_mul_hi_i32 s5, s34, 0x1200
	s_add_u32 s4, s50, s4
	v_pk_mul_f32 v[0:1], v[40:41], v[0:1] op_sel:[1,0] op_sel_hi:[0,0]
	v_mov_b32_e32 v2, v3
	s_addc_u32 s5, s51, s5
	s_lshl_b32 s8, s16, 5
	v_lshrrev_b32_e32 v47, 1, v52
	v_mov_b32_e32 v39, v45
	v_pk_fma_f32 v[44:45], v[40:41], v[2:3], v[0:1] op_sel_hi:[1,0,1]
	v_pk_fma_f32 v[6:7], v[40:41], v[2:3], v[0:1] op_sel_hi:[1,0,1] neg_lo:[0,0,1] neg_hi:[0,0,1]
	s_add_u32 s4, s4, s8
	v_mul_u32_u24_e32 v0, 0x900, v47
	v_lshlrev_b32_e32 v2, 3, v42
	s_addc_u32 s5, s5, 0
	v_lshlrev_b32_e32 v200, 1, v0
	v_and_b32_e32 v48, 8, v2
	v_lshl_add_u64 v[0:1], s[4:5], 0, v[200:201]
	v_lshlrev_b32_e32 v200, 1, v48
	v_lshl_add_u64 v[0:1], v[0:1], 0, v[200:201]
	s_mov_b64 s[4:5], 0x9919800
	v_mov_b32_e32 v7, v45
	s_mul_i32 s31, s35, 0x1240
	v_lshl_add_u64 v[40:41], v[0:1], 0, s[4:5]
	s_cmp_lt_i32 s35, 3
	v_cmp_gt_u32_e32 vcc, 16, v52
	s_cbranch_scc0 .LBB0_468
	v_mov_b32_e32 v200, v201
	v_mov_b64_e32 v[0:1], v[200:201]
	v_mov_b64_e32 v[2:3], v[200:201]
	s_and_saveexec_b64 s[4:5], vcc
	s_cbranch_execz .LBB0_460
	v_mad_i64_i32 v[0:1], s[8:9], s20, v242, v[40:41]
	global_load_dwordx4 v[0:3], v[0:1], off

.LBB0_468:
	v_mul_f32_e32 v1, 0x43f00000, v46
	v_and_b32_e32 v2, 0x7fffffff, v1
	s_brev_b32 s4, 18
	v_lshrrev_b32_e32 v0, 23, v2
	v_and_b32_e32 v3, 0x7fffff, v2
	v_cmp_nlt_f32_e64 s[4:5], |v1|, s4
	v_add_u32_e32 v35, 0xffffff88, v0
	v_or_b32_e32 v33, 0x800000, v3
	s_waitcnt lgkmcnt(0)
	s_barrier
	s_and_saveexec_b64 s[8:9], s[4:5]
	s_xor_b64 s[14:15], exec, s[8:9]
	s_cbranch_execz .LBB0_470
	s_mov_b32 s12, 0xfe5163ab
	v_mad_u64_u32 v[44:45], s[12:13], v33, s12, 0
	v_mov_b32_e32 v200, v45
	s_mov_b32 s12, 0x3c439041
	v_mad_u64_u32 v[50:51], s[12:13], v33, s12, v[200:201]
	v_mov_b32_e32 v200, v51
	s_mov_b32 s12, 0xdb629599
	v_mad_u64_u32 v[54:55], s[12:13], v33, s12, v[200:201]
	v_cmp_lt_u32_e32 vcc, 63, v35
	v_mov_b32_e32 v200, v55
	s_mov_b32 s12, 0xf534ddc0
	v_cndmask_b32_e32 v0, 0, v234, vcc
	v_mad_u64_u32 v[56:57], s[12:13], v33, s12, v[200:201]
	v_add_u32_e32 v0, v0, v35
	v_mov_b32_e32 v200, v57
	s_mov_b32 s12, 0xfc2757d1
	v_cmp_lt_u32_e64 s[8:9], 31, v0
	v_mad_u64_u32 v[58:59], s[12:13], v33, s12, v[200:201]
	s_nop 0
	v_cndmask_b32_e64 v3, 0, v235, s[8:9]
	v_mov_b32_e32 v200, v59
	s_mov_b32 s12, 0x4e441529
	v_add_u32_e32 v0, v3, v0
	v_mad_u64_u32 v[60:61], s[12:13], v33, s12, v[200:201]
	v_cmp_lt_u32_e64 s[10:11], 31, v0
	v_mov_b32_e32 v200, v61
	s_mov_b32 s12, 0xa2f9836e
	v_cndmask_b32_e64 v3, 0, v235, s[10:11]
	v_mad_u64_u32 v[62:63], s[12:13], v33, s12, v[200:201]
	v_add_u32_e32 v0, v3, v0
	v_cndmask_b32_e32 v3, v60, v56, vcc
	v_cndmask_b32_e32 v45, v62, v58, vcc
	v_cndmask_b32_e32 v49, v63, v60, vcc
	v_cndmask_b32_e64 v46, v45, v3, s[8:9]
	v_cndmask_b32_e64 v45, v49, v45, s[8:9]
	v_cndmask_b32_e32 v49, v58, v54, vcc
	v_cndmask_b32_e64 v3, v3, v49, s[8:9]
	v_cndmask_b32_e64 v45, v45, v46, s[10:11]
	v_cndmask_b32_e64 v46, v46, v3, s[10:11]
	v_sub_u32_e32 v51, 32, v0
	v_alignbit_b32 v53, v45, v46, v51
	v_cmp_eq_u32_e64 s[12:13], 0, v0
	v_cndmask_b32_e32 v44, v54, v44, vcc
	s_nop 0
	v_cndmask_b32_e64 v0, v53, v45, s[12:13]
	v_cndmask_b32_e32 v45, v56, v50, vcc
	v_cndmask_b32_e64 v49, v49, v45, s[8:9]
	v_cndmask_b32_e64 v3, v3, v49, s[10:11]
	v_alignbit_b32 v50, v46, v3, v51
	v_cndmask_b32_e64 v44, v45, v44, s[8:9]
	v_cndmask_b32_e64 v46, v50, v46, s[12:13]
	v_bfe_u32 v55, v0, 29, 1
	v_cndmask_b32_e64 v44, v49, v44, s[10:11]
	v_alignbit_b32 v50, v0, v46, 30
	v_sub_u32_e32 v56, 0, v55
	v_alignbit_b32 v45, v3, v44, v51
	v_xor_b32_e32 v50, v50, v56
	v_cndmask_b32_e64 v3, v45, v3, s[12:13]
	v_alignbit_b32 v45, v46, v3, 30
	v_ffbh_u32_e32 v46, v50
	v_min_u32_e32 v46, 32, v46
	v_alignbit_b32 v3, v3, v44, 30
	v_xor_b32_e32 v45, v45, v56
	v_sub_u32_e32 v49, 31, v46
	v_xor_b32_e32 v3, v3, v56
	v_alignbit_b32 v50, v50, v45, v49
	v_alignbit_b32 v3, v45, v3, v49
	v_alignbit_b32 v44, v50, v3, 9
	v_ffbh_u32_e32 v45, v44
	v_min_u32_e32 v45, 32, v45
	v_lshrrev_b32_e32 v53, 29, v0
	v_not_b32_e32 v49, v45
	v_alignbit_b32 v3, v44, v3, v49
	v_lshlrev_b32_e32 v44, 31, v53
	v_or_b32_e32 v49, 0x33000000, v44
	v_add_lshl_u32 v45, v45, v46, 23
	v_lshrrev_b32_e32 v3, 9, v3
	v_sub_u32_e32 v45, v49, v45
	v_or_b32_e32 v44, 0.5, v44
	v_lshlrev_b32_e32 v46, 23, v46
	v_or_b32_e32 v3, v45, v3
	v_lshrrev_b32_e32 v45, 9, v50
	v_sub_u32_e32 v44, v44, v46
	v_or_b32_e32 v44, v45, v44
	v_mul_f32_e32 v45, 0x3fc90fda, v44
	s_mov_b32 s8, 0x3fc90fda
	v_fma_f32 v46, v44, s8, -v45
	v_fmac_f32_e32 v46, 0x33a22168, v44
	v_fmac_f32_e32 v46, 0x3fc90fda, v3
	v_lshrrev_b32_e32 v0, 30, v0
	v_add_f32_e32 v3, v45, v46
	v_add_u32_e32 v0, v55, v0

.LBB0_475:
	v_mul_f32_e32 v33, 0x43f00000, v43
	v_mul_f32_e32 v35, 0x3fb8aa3b, v33
	s_mov_b32 s4, 0x3fb8aa3b
	v_fma_f32 v43, v33, s4, -v35
	v_rndne_f32_e32 v44, v35
	v_fmac_f32_e32 v43, 0x32a5705f, v33
	v_sub_f32_e32 v35, v35, v44
	v_add_f32_e32 v35, v35, v43
	v_cvt_i32_f32_e32 v43, v44
	v_exp_f32_e32 v35, v35
	s_mov_b32 s4, 0xc2ce8ed0
	v_cmp_ngt_f32_e32 vcc, s4, v33
	s_mov_b32 s4, 0x42b17218
	v_ldexp_f32 v35, v35, v43
	v_cndmask_b32_e32 v35, 0, v35, vcc
	v_cmp_nlt_f32_e32 vcc, s4, v33
	s_brev_b32 s4, 1
	v_mov_b32_e32 v44, 0
	v_cndmask_b32_e32 v33, v233, v35, vcc
	v_mul_f32_e32 v35, v3, v3
	v_fmamk_f32 v43, v35, 0xb94c1982, v224
	v_fmaak_f32 v43, v35, v43, 0xbe2aaa9d
	v_mul_f32_e32 v43, v35, v43
	v_fmac_f32_e32 v3, v3, v43
	v_fmamk_f32 v43, v35, 0x37d75334, v226
	v_fmaak_f32 v43, v35, v43, 0x3d2aabf7
	v_fmaak_f32 v43, v35, v43, 0xbf000004
	v_fma_f32 v35, v35, v43, 1.0
	v_and_b32_e32 v43, 1, v0
	v_cmp_eq_u32_e32 vcc, 0, v43
	v_lshlrev_b32_e32 v0, 30, v0
	s_nop 0
	v_cndmask_b32_e64 v3, -v3, v35, vcc
	v_bitop3_b32 v0, v0, v3, s4 bitop3:0x6c
	v_mul_f32_e32 v3, v45, v45
	v_fmamk_f32 v35, v3, 0xb94c1982, v224
	v_fmaak_f32 v35, v3, v35, 0xbe2aaa9d
	s_movk_i32 s4, 0x1f8
	v_mul_f32_e32 v35, v3, v35
	v_cmp_class_f32_e64 vcc, v1, s4
	v_xor_b32_e32 v1, v2, v1
	v_lshlrev_b32_e32 v2, 30, v46
	v_fmac_f32_e32 v45, v45, v35
	v_fmamk_f32 v35, v3, 0x37d75334, v226
	v_and_b32_e32 v2, 0x80000000, v2
	v_fmaak_f32 v35, v3, v35, 0x3d2aabf7
	v_xor_b32_e32 v1, v1, v2
	v_and_b32_e32 v2, 1, v46
	v_fmaak_f32 v35, v3, v35, 0xbf000004
	v_fma_f32 v3, v3, v35, 1.0
	v_cmp_eq_u32_e64 s[8:9], 0, v2
	v_cndmask_b32_e32 v0, v236, v0, vcc
	v_mul_f32_e32 v0, v33, v0
	v_cndmask_b32_e64 v2, v3, v45, s[8:9]
	v_xor_b32_e32 v1, v1, v2
	v_cndmask_b32_e32 v1, v236, v1, vcc
	v_mul_f32_e32 v2, v33, v1
	v_mov_b32_e32 v1, v0
	v_mov_b32_e32 v3, v2
	v_lshl_add_u32 v33, v52, 3, v243
	v_mov_b32_e32 v45, v44
